# mixer-B attention: next unit's Q and six K/V tiles prefetched into registers under the current unit's softmax/PV; band blocks outside the window skipped per wave parity
# speedup vs baseline: 1.0092x; 1.0060x over previous
.LBB0_308:
	s_add_i32 s3, s74, 0x5ff
	s_ashr_i32 s4, s3, 31
	s_abs_i32 s3, s3
	s_mul_i32 s1, s3, s1
	s_mul_hi_u32 s0, s3, s0
	s_add_i32 s0, s0, s1
	s_mul_i32 s1, s0, s16
	s_sub_i32 s1, s3, s1
	s_xor_b32 s4, s4, s17
	s_add_i32 s3, s0, 1
	s_sub_i32 s5, s1, s16
	s_cmp_ge_u32 s1, s16
	s_cselect_b32 s0, s3, s0
	s_cselect_b32 s1, s5, s1
	s_add_i32 s3, s0, 1
	s_cmp_ge_u32 s1, s16
	s_cselect_b32 s0, s3, s0
	s_xor_b32 s0, s0, s4
	s_sub_i32 s3, s0, s4
	s_cmp_lt_i32 s3, 1
	s_cbranch_scc1 .LBB0_392
	v_and_b32_e32 v1, 63, v0
	v_and_b32_e32 v180, 31, v0
	v_bfe_u32 v181, v0, 5, 1
	v_readfirstlane_b32 s31, v0
	s_nop 3
	s_lshr_b32 s31, s31, 6
	s_lshr_b32 s29, s31, 1
	s_mul_i32 s30, s29, 0x4800
	v_and_b32_e32 v189, 0x13, v180
	v_and_b32_e32 v190, 4, v180
	v_and_b32_e32 v191, 8, v180
	v_lshlrev_b32_e32 v190, 1, v190
	v_lshrrev_b32_e32 v191, 1, v191
	v_or3_b32 v189, v189, v190, v191
	v_mul_u32_u24_e32 v183, 0x90, v189
	v_lshl_add_u32 v183, v181, 4, v183
	v_add_u32_e32 v183, s30, v183
	v_bfe_u32 v189, v0, 2, 2
	v_lshl_add_u32 v189, v181, 3, v189
	v_mul_u32_u24_e32 v184, 0x90, v189
	v_bfe_u32 v190, v0, 4, 1
	v_lshl_add_u32 v184, v190, 5, v184
	v_and_b32_e32 v190, 3, v0
	v_lshl_add_u32 v184, v190, 3, v184
	v_add_u32_e32 v184, s30, v184
	v_lshrrev_b32_e32 v187, 3, v0
	v_and_b32_e32 v190, 7, v0
	v_lshlrev_b32_e32 v188, 4, v190
	v_mul_u32_u24_e32 v185, 0x90, v187
	v_add_u32_e32 v185, v185, v188
	v_add_u32_e32 v206, 0xd800, v185
	s_and_b32 s28, s31, 1
	s_lshl_b32 s28, s28, 5
	v_lshlrev_b32_e32 v190, 3, v181
	v_sub_u32_e32 v186, v180, v190
	v_add_u32_e32 v186, s28, v186
	v_mov_b32_e32 v198, 0xff800000
	s_mov_b32 s20, s3
	s_mul_i32 s21, s3, s14
	s_cmpk_gt_i32 s21, 0x5ff
	s_cbranch_scc1 .Lmb_done
	s_and_b32 s25, s21, 63
	s_lshr_b32 s26, s21, 6
	s_and_b32 s11, s26, 3
	s_lshr_b32 s27, s26, 2
	s_cmp_ge_u32 s27, 3
	s_cselect_b32 s12, 1, 0
	s_mul_i32 s10, s12, 3
	s_sub_i32 s10, s27, s10
	s_lshl_b32 s6, s10, 1
	s_sub_i32 s13, 6, s6
	s_lshr_b32 s7, s25, s13
	s_lshl_b32 s8, 1, s13
	s_add_i32 s8, s8, -1
	s_and_b32 s8, s25, s8
	s_lshl_b32 s8, s8, 8
	s_lshr_b32 s9, 0x4000, s6
	s_add_i32 s15, s9, -1
	s_mul_i32 s28, s12, 0x6000000
	s_add_u32 s4, s94, 0x7800000
	s_addc_u32 s5, s95, 0
	s_add_u32 s4, s4, s28
	s_addc_u32 s5, s5, 0
	s_lshl_b32 s22, s10, 9
	s_lshl_b32 s23, s11, 7
	s_add_i32 s22, s22, s23
	s_add_i32 s22, s22, 0x600
	s_add_i32 s23, s22, 0x600
	s_add_i32 s24, s22, 0xc00
	s_add_u32 s34, s4, s23
	s_addc_u32 s35, s5, 0
	s_add_u32 s36, s4, s24
	s_addc_u32 s37, s5, 0
	s_add_i32 s26, s8, -64
	s_lshl_b32 s25, s31, 5
	s_add_i32 s25, s25, s8
	v_add_u32_e32 v189, s25, v180
	v_lshlrev_b32_e32 v189, s6, v189
	v_add_u32_e32 v189, s7, v189
	v_mul_u32_u24_e32 v190, 0x1800, v189
	v_lshl_add_u32 v190, v181, 4, v190
	v_add_u32_e32 v190, s22, v190
	global_load_dwordx4 v[100:103], v190, s[4:5]
	global_load_dwordx4 v[104:107], v190, s[4:5] offset:32
	global_load_dwordx4 v[108:111], v190, s[4:5] offset:64
	global_load_dwordx4 v[112:115], v190, s[4:5] offset:96
	v_add_u32_e32 v200, s26, v187
	v_med3_i32 v200, v200, 0, s15
	v_lshlrev_b32_e32 v200, s6, v200
	v_add_u32_e32 v200, s7, v200
	v_mul_u32_u24_e32 v200, 0x1800, v200
	v_add_u32_e32 v200, v200, v188
	global_load_dwordx4 v[82:85], v200, s[34:35]
	global_load_dwordx4 v[86:89], v200, s[36:37]
	v_add_u32_e32 v201, s26, v187
	v_add_u32_e32 v201, 64, v201
	v_med3_i32 v201, v201, 0, s15
	v_lshlrev_b32_e32 v201, s6, v201
	v_add_u32_e32 v201, s7, v201
	v_mul_u32_u24_e32 v201, 0x1800, v201
	v_add_u32_e32 v201, v201, v188
	global_load_dwordx4 v[90:93], v201, s[34:35]
	global_load_dwordx4 v[94:97], v201, s[36:37]
	v_add_u32_e32 v202, s26, v187
	v_add_u32_e32 v202, 128, v202
	v_med3_i32 v202, v202, 0, s15
	v_lshlrev_b32_e32 v202, s6, v202
	v_add_u32_e32 v202, s7, v202
	v_mul_u32_u24_e32 v202, 0x1800, v202
	v_add_u32_e32 v202, v202, v188
	global_load_dwordx4 v[214:217], v202, s[34:35]
	global_load_dwordx4 v[218:221], v202, s[36:37]
	v_add_u32_e32 v203, s26, v187
	v_add_u32_e32 v203, 192, v203
	v_med3_i32 v203, v203, 0, s15
	v_lshlrev_b32_e32 v203, s6, v203
	v_add_u32_e32 v203, s7, v203
	v_mul_u32_u24_e32 v203, 0x1800, v203
	v_add_u32_e32 v203, v203, v188
	global_load_dwordx4 v[222:225], v203, s[34:35]
	global_load_dwordx4 v[226:229], v203, s[36:37]
	v_add_u32_e32 v204, s26, v187
	v_add_u32_e32 v204, 256, v204
	v_med3_i32 v204, v204, 0, s15
	v_lshlrev_b32_e32 v204, s6, v204
	v_add_u32_e32 v204, s7, v204
	v_mul_u32_u24_e32 v204, 0x1800, v204
	v_add_u32_e32 v204, v204, v188
	global_load_dwordx4 v[234:237], v204, s[34:35]
	global_load_dwordx4 v[238:241], v204, s[36:37]
	v_add_u32_e32 v205, s26, v187
	v_add_u32_e32 v205, 320, v205
	v_med3_i32 v205, v205, 0, s15
	v_lshlrev_b32_e32 v205, s6, v205
	v_add_u32_e32 v205, s7, v205
	v_mul_u32_u24_e32 v205, 0x1800, v205
	v_add_u32_e32 v205, v205, v188
	global_load_dwordx4 v[242:245], v205, s[34:35]
	global_load_dwordx4 v[246:249], v205, s[36:37]
.Lmb_unit:
	s_and_b32 s54, s21, 63
	s_lshr_b32 s55, s21, 6
	s_and_b32 s56, s55, 3
	s_lshr_b32 s57, s55, 2
	s_cmp_ge_u32 s57, 3
	s_cselect_b32 s58, 1, 0
	s_mul_i32 s59, s58, 3
	s_sub_i32 s59, s57, s59
	s_lshl_b32 s60, s59, 1
	s_sub_i32 s61, 6, s60
	s_lshr_b32 s62, s54, s61
	s_lshl_b32 s63, 1, s61
	s_add_i32 s63, s63, -1
	s_and_b32 s63, s54, s63
	s_lshl_b32 s63, s63, 8
	s_lshr_b32 s64, 0x4000, s60
	s_lshl_b32 s28, s59, 24
	s_lshl_b32 s38, s58, 23
	s_add_i32 s28, s28, s38
	s_lshl_b32 s38, s56, 7
	s_add_i32 s28, s28, s38
	s_add_u32 s16, s94, 0x3800000
	s_addc_u32 s17, s95, 0
	s_add_u32 s16, s16, s28
	s_addc_u32 s17, s17, 0
	s_lshl_b32 s28, s59, 19
	s_lshl_b32 s38, s58, 18
	s_add_i32 s28, s28, s38
	s_lshl_b32 s38, s56, 2
	s_add_i32 s28, s28, s38
	s_add_u32 s18, s94, 0x6800000
	s_addc_u32 s19, s95, 0
	s_add_u32 s18, s18, s28
	s_addc_u32 s19, s19, 0
	s_lshl_b32 s65, s31, 5
	s_add_i32 s65, s65, s63
	v_add_u32_e32 v199, s65, v180
	v_lshlrev_b32_e32 v199, s60, v199
	v_add_u32_e32 v199, s62, v199
	s_add_i32 s66, s63, -64
	s_lshl_b32 s67, s29, 6
	s_add_i32 s67, s67, s66
	s_add_i32 s28, s67, 0
	s_cmp_ge_i32 s28, 0
	s_cselect_b32 s50, 1, 0
	s_cmp_lt_i32 s28, s64
	s_cselect_b32 s50, s50, 0
	s_add_i32 s28, s67, 64
	s_cmp_ge_i32 s28, 0
	s_cselect_b32 s51, 1, 0
	s_cmp_lt_i32 s28, s64
	s_cselect_b32 s51, s51, 0
	s_add_i32 s28, s67, 128
	s_cmp_ge_i32 s28, 0
	s_cselect_b32 s52, 1, 0
	s_cmp_lt_i32 s28, s64
	s_cselect_b32 s52, s52, 0
	s_waitcnt vmcnt(0)
	s_barrier
	ds_write_b128 v185, v[82:85]
	ds_write_b128 v185, v[86:89] offset:9216
	ds_write_b128 v185, v[90:93] offset:18432
	ds_write_b128 v185, v[94:97] offset:27648
	ds_write_b128 v185, v[214:217] offset:36864
	ds_write_b128 v185, v[218:221] offset:46080
	ds_write_b128 v206, v[222:225]
	ds_write_b128 v206, v[226:229] offset:9216
	ds_write_b128 v206, v[234:237] offset:18432
	ds_write_b128 v206, v[238:241] offset:27648
	ds_write_b128 v206, v[242:245] offset:36864
	ds_write_b128 v206, v[246:249] offset:46080
	s_waitcnt lgkmcnt(0)
	s_barrier
	s_bitcmp1_b32 s31, 0
	s_cbranch_scc1 .Lmb_odd
	ds_read_b128 v[148:151], v183
	ds_read_b128 v[152:155], v183 offset:32
	ds_read_b128 v[156:159], v183 offset:64
	ds_read_b128 v[160:163], v183 offset:96
	ds_read_b128 v[164:167], v183 offset:4608
	ds_read_b128 v[168:171], v183 offset:4640
	ds_read_b128 v[172:175], v183 offset:4672
	ds_read_b128 v[176:179], v183 offset:4704
	s_waitcnt lgkmcnt(7)
	v_mfma_f32_32x32x16_bf16 v[2:17], v[148:151], v[100:103], 0
	s_waitcnt lgkmcnt(6)
	v_mfma_f32_32x32x16_bf16 v[2:17], v[152:155], v[104:107], v[2:17]
	s_waitcnt lgkmcnt(5)
	v_mfma_f32_32x32x16_bf16 v[2:17], v[156:159], v[108:111], v[2:17]
	s_waitcnt lgkmcnt(4)
	v_mfma_f32_32x32x16_bf16 v[2:17], v[160:163], v[112:115], v[2:17]
	ds_read_b128 v[148:151], v183 offset:18432
	ds_read_b128 v[152:155], v183 offset:18464
	ds_read_b128 v[156:159], v183 offset:18496
	ds_read_b128 v[160:163], v183 offset:18528
	s_waitcnt lgkmcnt(7)
	v_mfma_f32_32x32x16_bf16 v[18:33], v[164:167], v[100:103], 0
	s_waitcnt lgkmcnt(6)
	v_mfma_f32_32x32x16_bf16 v[18:33], v[168:171], v[104:107], v[18:33]
	s_waitcnt lgkmcnt(5)
	v_mfma_f32_32x32x16_bf16 v[18:33], v[172:175], v[108:111], v[18:33]
	s_waitcnt lgkmcnt(4)
	v_mfma_f32_32x32x16_bf16 v[18:33], v[176:179], v[112:115], v[18:33]
	ds_read_b128 v[164:167], v183 offset:23040
	ds_read_b128 v[168:171], v183 offset:23072
	ds_read_b128 v[172:175], v183 offset:23104
	ds_read_b128 v[176:179], v183 offset:23136
	s_waitcnt lgkmcnt(7)
	v_mfma_f32_32x32x16_bf16 v[34:49], v[148:151], v[100:103], 0
	s_waitcnt lgkmcnt(6)
	v_mfma_f32_32x32x16_bf16 v[34:49], v[152:155], v[104:107], v[34:49]
	s_waitcnt lgkmcnt(5)
	v_mfma_f32_32x32x16_bf16 v[34:49], v[156:159], v[108:111], v[34:49]
	s_waitcnt lgkmcnt(4)
	v_mfma_f32_32x32x16_bf16 v[34:49], v[160:163], v[112:115], v[34:49]
	ds_read_b128 v[148:151], v183 offset:36864
	ds_read_b128 v[152:155], v183 offset:36896
	ds_read_b128 v[156:159], v183 offset:36928
	ds_read_b128 v[160:163], v183 offset:36960
	s_waitcnt lgkmcnt(7)
	v_mfma_f32_32x32x16_bf16 v[50:65], v[164:167], v[100:103], 0
	s_waitcnt lgkmcnt(6)
	v_mfma_f32_32x32x16_bf16 v[50:65], v[168:171], v[104:107], v[50:65]
	s_waitcnt lgkmcnt(5)
	v_mfma_f32_32x32x16_bf16 v[50:65], v[172:175], v[108:111], v[50:65]
	s_waitcnt lgkmcnt(4)
	v_mfma_f32_32x32x16_bf16 v[50:65], v[176:179], v[112:115], v[50:65]
	s_waitcnt lgkmcnt(3)
	v_mfma_f32_32x32x16_bf16 v[66:81], v[148:151], v[100:103], 0
	s_waitcnt lgkmcnt(2)
	v_mfma_f32_32x32x16_bf16 v[66:81], v[152:155], v[104:107], v[66:81]
	s_waitcnt lgkmcnt(1)
	v_mfma_f32_32x32x16_bf16 v[66:81], v[156:159], v[108:111], v[66:81]
	s_waitcnt lgkmcnt(0)
	v_mfma_f32_32x32x16_bf16 v[66:81], v[160:163], v[112:115], v[66:81]
	s_add_i32 s33, s21, 1
	s_cmp_le_u32 s20, 1
	s_cbranch_scc1 .Lmb_nopf0
	s_cmpk_gt_i32 s33, 0x5ff
	s_cbranch_scc1 .Lmb_nopf0
	s_and_b32 s25, s33, 63
	s_lshr_b32 s26, s33, 6
	s_and_b32 s11, s26, 3
	s_lshr_b32 s27, s26, 2
	s_cmp_ge_u32 s27, 3
	s_cselect_b32 s12, 1, 0
	s_mul_i32 s10, s12, 3
	s_sub_i32 s10, s27, s10
	s_lshl_b32 s6, s10, 1
	s_sub_i32 s13, 6, s6
	s_lshr_b32 s7, s25, s13
	s_lshl_b32 s8, 1, s13
	s_add_i32 s8, s8, -1
	s_and_b32 s8, s25, s8
	s_lshl_b32 s8, s8, 8
	s_lshr_b32 s9, 0x4000, s6
	s_add_i32 s15, s9, -1
	s_mul_i32 s28, s12, 0x6000000
	s_add_u32 s4, s94, 0x7800000
	s_addc_u32 s5, s95, 0
	s_add_u32 s4, s4, s28
	s_addc_u32 s5, s5, 0
	s_lshl_b32 s22, s10, 9
	s_lshl_b32 s23, s11, 7
	s_add_i32 s22, s22, s23
	s_add_i32 s22, s22, 0x600
	s_add_i32 s23, s22, 0x600
	s_add_i32 s24, s22, 0xc00
	s_add_u32 s34, s4, s23
	s_addc_u32 s35, s5, 0
	s_add_u32 s36, s4, s24
	s_addc_u32 s37, s5, 0
	s_add_i32 s26, s8, -64
	s_lshl_b32 s25, s31, 5
	s_add_i32 s25, s25, s8
	v_add_u32_e32 v189, s25, v180
	v_lshlrev_b32_e32 v189, s6, v189
	v_add_u32_e32 v189, s7, v189
	v_mul_u32_u24_e32 v190, 0x1800, v189
	v_lshl_add_u32 v190, v181, 4, v190
	v_add_u32_e32 v190, s22, v190
	global_load_dwordx4 v[100:103], v190, s[4:5]
	global_load_dwordx4 v[104:107], v190, s[4:5] offset:32
	global_load_dwordx4 v[108:111], v190, s[4:5] offset:64
	global_load_dwordx4 v[112:115], v190, s[4:5] offset:96
	v_add_u32_e32 v200, s26, v187
	v_med3_i32 v200, v200, 0, s15
	v_lshlrev_b32_e32 v200, s6, v200
	v_add_u32_e32 v200, s7, v200
	v_mul_u32_u24_e32 v200, 0x1800, v200
	v_add_u32_e32 v200, v200, v188
	global_load_dwordx4 v[82:85], v200, s[34:35]
	global_load_dwordx4 v[86:89], v200, s[36:37]
	v_add_u32_e32 v201, s26, v187
	v_add_u32_e32 v201, 64, v201
	v_med3_i32 v201, v201, 0, s15
	v_lshlrev_b32_e32 v201, s6, v201
	v_add_u32_e32 v201, s7, v201
	v_mul_u32_u24_e32 v201, 0x1800, v201
	v_add_u32_e32 v201, v201, v188
	global_load_dwordx4 v[90:93], v201, s[34:35]
	global_load_dwordx4 v[94:97], v201, s[36:37]
	v_add_u32_e32 v202, s26, v187
	v_add_u32_e32 v202, 128, v202
	v_med3_i32 v202, v202, 0, s15
	v_lshlrev_b32_e32 v202, s6, v202
	v_add_u32_e32 v202, s7, v202
	v_mul_u32_u24_e32 v202, 0x1800, v202
	v_add_u32_e32 v202, v202, v188
	global_load_dwordx4 v[214:217], v202, s[34:35]
	global_load_dwordx4 v[218:221], v202, s[36:37]
	v_add_u32_e32 v203, s26, v187
	v_add_u32_e32 v203, 192, v203
	v_med3_i32 v203, v203, 0, s15
	v_lshlrev_b32_e32 v203, s6, v203
	v_add_u32_e32 v203, s7, v203
	v_mul_u32_u24_e32 v203, 0x1800, v203
	v_add_u32_e32 v203, v203, v188
	global_load_dwordx4 v[222:225], v203, s[34:35]
	global_load_dwordx4 v[226:229], v203, s[36:37]
	v_add_u32_e32 v204, s26, v187
	v_add_u32_e32 v204, 256, v204
	v_med3_i32 v204, v204, 0, s15
	v_lshlrev_b32_e32 v204, s6, v204
	v_add_u32_e32 v204, s7, v204
	v_mul_u32_u24_e32 v204, 0x1800, v204
	v_add_u32_e32 v204, v204, v188
	global_load_dwordx4 v[234:237], v204, s[34:35]
	global_load_dwordx4 v[238:241], v204, s[36:37]
	v_add_u32_e32 v205, s26, v187
	v_add_u32_e32 v205, 320, v205
	v_med3_i32 v205, v205, 0, s15
	v_lshlrev_b32_e32 v205, s6, v205
	v_add_u32_e32 v205, s7, v205
	v_mul_u32_u24_e32 v205, 0x1800, v205
	v_add_u32_e32 v205, v205, v188
	global_load_dwordx4 v[242:245], v205, s[34:35]
	global_load_dwordx4 v[246:249], v205, s[36:37]
.Lmb_nopf0:
	s_cmp_lg_u32 s50, 0
	s_cbranch_scc1 .Lmb_tv0_0
	s_nop 7
	s_nop 7
	v_mov_b32_e32 v2, v198
	v_mov_b32_e32 v3, v198
	v_mov_b32_e32 v4, v198
	v_mov_b32_e32 v5, v198
	v_mov_b32_e32 v6, v198
	v_mov_b32_e32 v7, v198
	v_mov_b32_e32 v8, v198
	v_mov_b32_e32 v9, v198
	v_mov_b32_e32 v10, v198
	v_mov_b32_e32 v11, v198
	v_mov_b32_e32 v12, v198
	v_mov_b32_e32 v13, v198
	v_mov_b32_e32 v14, v198
	v_mov_b32_e32 v15, v198
	v_mov_b32_e32 v16, v198
	v_mov_b32_e32 v17, v198
	v_mov_b32_e32 v18, v198
	v_mov_b32_e32 v19, v198
	v_mov_b32_e32 v20, v198
	v_mov_b32_e32 v21, v198
	v_mov_b32_e32 v22, v198
	v_mov_b32_e32 v23, v198
	v_mov_b32_e32 v24, v198
	v_mov_b32_e32 v25, v198
	v_mov_b32_e32 v26, v198
	v_mov_b32_e32 v27, v198
	v_mov_b32_e32 v28, v198
	v_mov_b32_e32 v29, v198
	v_mov_b32_e32 v30, v198
	v_mov_b32_e32 v31, v198
	v_mov_b32_e32 v32, v198
	v_mov_b32_e32 v33, v198

.Lmb_tv0_2:
	s_nop 7
	s_nop 4
	v_cmp_ge_i32_e64 s[40:41], 0, v186
	v_cmp_ge_i32_e64 s[42:43], 1, v186
	v_cmp_ge_i32_e64 s[44:45], 2, v186
	v_cmp_ge_i32_e64 s[46:47], 3, v186
	v_cndmask_b32_e64 v2, v198, v2, s[40:41]
	v_cndmask_b32_e64 v3, v198, v3, s[42:43]
	v_cndmask_b32_e64 v4, v198, v4, s[44:45]
	v_cndmask_b32_e64 v5, v198, v5, s[46:47]
	v_cmp_ge_i32_e64 s[40:41], 4, v186
	v_cmp_ge_i32_e64 s[42:43], 5, v186
	v_cmp_ge_i32_e64 s[44:45], 6, v186
	v_cmp_ge_i32_e64 s[46:47], 7, v186
	v_cndmask_b32_e64 v6, v198, v6, s[40:41]
	v_cndmask_b32_e64 v7, v198, v7, s[42:43]
	v_cndmask_b32_e64 v8, v198, v8, s[44:45]
	v_cndmask_b32_e64 v9, v198, v9, s[46:47]
	v_cmp_ge_i32_e64 s[40:41], 16, v186
	v_cmp_ge_i32_e64 s[42:43], 17, v186
	v_cmp_ge_i32_e64 s[44:45], 18, v186
	v_cmp_ge_i32_e64 s[46:47], 19, v186
	v_cndmask_b32_e64 v10, v198, v10, s[40:41]
	v_cndmask_b32_e64 v11, v198, v11, s[42:43]
	v_cndmask_b32_e64 v12, v198, v12, s[44:45]
	v_cndmask_b32_e64 v13, v198, v13, s[46:47]
	v_cmp_ge_i32_e64 s[40:41], 20, v186
	v_cmp_ge_i32_e64 s[42:43], 21, v186
	v_cmp_ge_i32_e64 s[44:45], 22, v186
	v_cmp_ge_i32_e64 s[46:47], 23, v186
	v_cndmask_b32_e64 v14, v198, v14, s[40:41]
	v_cndmask_b32_e64 v15, v198, v15, s[42:43]
	v_cndmask_b32_e64 v16, v198, v16, s[44:45]
	v_cndmask_b32_e64 v17, v198, v17, s[46:47]
	v_cmp_le_i32_e64 s[40:41], 0, v186
	v_cmp_le_i32_e64 s[42:43], 1, v186
	v_cmp_le_i32_e64 s[44:45], 2, v186
	v_cmp_le_i32_e64 s[46:47], 3, v186
	v_cndmask_b32_e64 v66, v198, v66, s[40:41]
	v_cndmask_b32_e64 v67, v198, v67, s[42:43]
	v_cndmask_b32_e64 v68, v198, v68, s[44:45]
	v_cndmask_b32_e64 v69, v198, v69, s[46:47]
	v_cmp_le_i32_e64 s[40:41], 4, v186
	v_cmp_le_i32_e64 s[42:43], 5, v186
	v_cmp_le_i32_e64 s[44:45], 6, v186
	v_cmp_le_i32_e64 s[46:47], 7, v186
	v_cndmask_b32_e64 v70, v198, v70, s[40:41]
	v_cndmask_b32_e64 v71, v198, v71, s[42:43]
	v_cndmask_b32_e64 v72, v198, v72, s[44:45]
	v_cndmask_b32_e64 v73, v198, v73, s[46:47]
	v_cmp_le_i32_e64 s[40:41], 16, v186
	v_cmp_le_i32_e64 s[42:43], 17, v186
	v_cmp_le_i32_e64 s[44:45], 18, v186
	v_cmp_le_i32_e64 s[46:47], 19, v186
	v_cndmask_b32_e64 v74, v198, v74, s[40:41]
	v_cndmask_b32_e64 v75, v198, v75, s[42:43]
	v_cndmask_b32_e64 v76, v198, v76, s[44:45]
	v_cndmask_b32_e64 v77, v198, v77, s[46:47]
	v_cmp_le_i32_e64 s[40:41], 20, v186
	v_cmp_le_i32_e64 s[42:43], 21, v186
	v_cmp_le_i32_e64 s[44:45], 22, v186
	v_cmp_le_i32_e64 s[46:47], 23, v186
	v_cndmask_b32_e64 v78, v198, v78, s[40:41]
	v_cndmask_b32_e64 v79, v198, v79, s[42:43]
	v_cndmask_b32_e64 v80, v198, v80, s[44:45]
	v_cndmask_b32_e64 v81, v198, v81, s[46:47]
	v_max3_f32 v192, v2, v3, v4
	v_max3_f32 v193, v5, v6, v7
	v_max3_f32 v192, v192, v8, v9
	v_max3_f32 v193, v193, v10, v11
	v_max3_f32 v192, v192, v12, v13
	v_max3_f32 v193, v193, v14, v15
	v_max3_f32 v192, v192, v16, v17
	v_max3_f32 v193, v193, v18, v19
	v_max3_f32 v192, v192, v20, v21
	v_max3_f32 v193, v193, v22, v23
	v_max3_f32 v192, v192, v24, v25
	v_max3_f32 v193, v193, v26, v27
	v_max3_f32 v192, v192, v28, v29
	v_max3_f32 v193, v193, v30, v31
	v_max3_f32 v192, v192, v32, v33
	v_max3_f32 v193, v193, v34, v35
	v_max3_f32 v192, v192, v36, v37
	v_max3_f32 v193, v193, v38, v39
	v_max3_f32 v192, v192, v40, v41
	v_max3_f32 v193, v193, v42, v43
	v_max3_f32 v192, v192, v44, v45
	v_max3_f32 v193, v193, v46, v47
	v_max3_f32 v192, v192, v48, v49
	v_max3_f32 v193, v193, v50, v51
	v_max3_f32 v192, v192, v52, v53
	v_max3_f32 v193, v193, v54, v55
	v_max3_f32 v192, v192, v56, v57
	v_max3_f32 v193, v193, v58, v59
	v_max3_f32 v192, v192, v60, v61
	v_max3_f32 v193, v193, v62, v63
	v_max3_f32 v192, v192, v64, v65
	v_max3_f32 v193, v193, v66, v67
	v_max3_f32 v192, v192, v68, v69
	v_max3_f32 v193, v193, v70, v71
	v_max3_f32 v192, v192, v72, v73
	v_max3_f32 v193, v193, v74, v75
	v_max3_f32 v192, v192, v76, v77
	v_max3_f32 v193, v193, v78, v79
	v_max3_f32 v192, v192, v80, v81
	v_max_f32_e32 v192, v192, v193
	v_mov_b32_e32 v193, v192
	s_nop 1
	v_permlane32_swap_b32_e32 v192, v193
	v_max_f32_e32 v192, v192, v193
	v_mov_b32_e32 v194, 0
	v_mov_b32_e32 v195, 0
	v_mov_b32_e32 v196, 0
	v_mov_b32_e32 v197, 0
	v_sub_f32_e32 v2, v2, v192
	v_sub_f32_e32 v3, v3, v192
	v_exp_f32_e32 v2, v2
	v_exp_f32_e32 v3, v3
	v_add_f32_e32 v194, v194, v2
	v_add_f32_e32 v195, v195, v3
	v_cvt_pk_bf16_f32 v2, v2, v3
	v_sub_f32_e32 v4, v4, v192
	v_sub_f32_e32 v5, v5, v192
	v_exp_f32_e32 v4, v4
	v_exp_f32_e32 v5, v5
	v_add_f32_e32 v196, v196, v4
	v_add_f32_e32 v197, v197, v5
	v_cvt_pk_bf16_f32 v3, v4, v5
	v_sub_f32_e32 v6, v6, v192
	v_sub_f32_e32 v7, v7, v192
	v_exp_f32_e32 v6, v6
	v_exp_f32_e32 v7, v7
	v_add_f32_e32 v194, v194, v6
	v_add_f32_e32 v195, v195, v7
	v_cvt_pk_bf16_f32 v4, v6, v7
	v_sub_f32_e32 v8, v8, v192
	v_sub_f32_e32 v9, v9, v192
	v_exp_f32_e32 v8, v8
	v_exp_f32_e32 v9, v9
	v_add_f32_e32 v196, v196, v8
	v_add_f32_e32 v197, v197, v9
	v_cvt_pk_bf16_f32 v5, v8, v9
	v_sub_f32_e32 v10, v10, v192
	v_sub_f32_e32 v11, v11, v192
	v_exp_f32_e32 v10, v10
	v_exp_f32_e32 v11, v11
	v_add_f32_e32 v194, v194, v10
	v_add_f32_e32 v195, v195, v11
	v_cvt_pk_bf16_f32 v10, v10, v11
	v_sub_f32_e32 v12, v12, v192
	v_sub_f32_e32 v13, v13, v192
	v_exp_f32_e32 v12, v12
	v_exp_f32_e32 v13, v13
	v_add_f32_e32 v196, v196, v12
	v_add_f32_e32 v197, v197, v13
	v_cvt_pk_bf16_f32 v11, v12, v13
	v_sub_f32_e32 v14, v14, v192
	v_sub_f32_e32 v15, v15, v192
	v_exp_f32_e32 v14, v14
	v_exp_f32_e32 v15, v15
	v_add_f32_e32 v194, v194, v14
	v_add_f32_e32 v195, v195, v15
	v_cvt_pk_bf16_f32 v12, v14, v15
	v_sub_f32_e32 v16, v16, v192
	v_sub_f32_e32 v17, v17, v192
	v_exp_f32_e32 v16, v16
	v_exp_f32_e32 v17, v17
	v_add_f32_e32 v196, v196, v16
	v_add_f32_e32 v197, v197, v17
	v_cvt_pk_bf16_f32 v13, v16, v17
	v_sub_f32_e32 v18, v18, v192
	v_sub_f32_e32 v19, v19, v192
	v_exp_f32_e32 v18, v18
	v_exp_f32_e32 v19, v19
	v_add_f32_e32 v194, v194, v18
	v_add_f32_e32 v195, v195, v19
	v_cvt_pk_bf16_f32 v18, v18, v19
	v_sub_f32_e32 v20, v20, v192
	v_sub_f32_e32 v21, v21, v192
	v_exp_f32_e32 v20, v20
	v_exp_f32_e32 v21, v21
	v_add_f32_e32 v196, v196, v20
	v_add_f32_e32 v197, v197, v21
	v_cvt_pk_bf16_f32 v19, v20, v21
	v_sub_f32_e32 v22, v22, v192
	v_sub_f32_e32 v23, v23, v192
	v_exp_f32_e32 v22, v22
	v_exp_f32_e32 v23, v23
	v_add_f32_e32 v194, v194, v22
	v_add_f32_e32 v195, v195, v23
	v_cvt_pk_bf16_f32 v20, v22, v23
	v_sub_f32_e32 v24, v24, v192
	v_sub_f32_e32 v25, v25, v192
	v_exp_f32_e32 v24, v24
	v_exp_f32_e32 v25, v25
	v_add_f32_e32 v196, v196, v24
	v_add_f32_e32 v197, v197, v25
	v_cvt_pk_bf16_f32 v21, v24, v25
	v_sub_f32_e32 v26, v26, v192
	v_sub_f32_e32 v27, v27, v192
	v_exp_f32_e32 v26, v26
	v_exp_f32_e32 v27, v27
	v_add_f32_e32 v194, v194, v26
	v_add_f32_e32 v195, v195, v27
	v_cvt_pk_bf16_f32 v26, v26, v27
	v_sub_f32_e32 v28, v28, v192
	v_sub_f32_e32 v29, v29, v192
	v_exp_f32_e32 v28, v28
	v_exp_f32_e32 v29, v29
	v_add_f32_e32 v196, v196, v28
	v_add_f32_e32 v197, v197, v29
	v_cvt_pk_bf16_f32 v27, v28, v29
	v_sub_f32_e32 v30, v30, v192
	v_sub_f32_e32 v31, v31, v192
	v_exp_f32_e32 v30, v30
	v_exp_f32_e32 v31, v31
	v_add_f32_e32 v194, v194, v30
	v_add_f32_e32 v195, v195, v31
	v_cvt_pk_bf16_f32 v28, v30, v31
	v_sub_f32_e32 v32, v32, v192
	v_sub_f32_e32 v33, v33, v192
	v_exp_f32_e32 v32, v32
	v_exp_f32_e32 v33, v33
	v_add_f32_e32 v196, v196, v32
	v_add_f32_e32 v197, v197, v33
	v_cvt_pk_bf16_f32 v29, v32, v33
	v_sub_f32_e32 v34, v34, v192
	v_sub_f32_e32 v35, v35, v192
	v_exp_f32_e32 v34, v34
	v_exp_f32_e32 v35, v35
	v_add_f32_e32 v194, v194, v34
	v_add_f32_e32 v195, v195, v35
	v_cvt_pk_bf16_f32 v34, v34, v35
	v_sub_f32_e32 v36, v36, v192
	v_sub_f32_e32 v37, v37, v192
	v_exp_f32_e32 v36, v36
	v_exp_f32_e32 v37, v37
	v_add_f32_e32 v196, v196, v36
	v_add_f32_e32 v197, v197, v37
	v_cvt_pk_bf16_f32 v35, v36, v37
	v_sub_f32_e32 v38, v38, v192
	v_sub_f32_e32 v39, v39, v192
	v_exp_f32_e32 v38, v38
	v_exp_f32_e32 v39, v39
	v_add_f32_e32 v194, v194, v38
	v_add_f32_e32 v195, v195, v39
	v_cvt_pk_bf16_f32 v36, v38, v39
	v_sub_f32_e32 v40, v40, v192
	v_sub_f32_e32 v41, v41, v192
	v_exp_f32_e32 v40, v40
	v_exp_f32_e32 v41, v41
	v_add_f32_e32 v196, v196, v40
	v_add_f32_e32 v197, v197, v41
	v_cvt_pk_bf16_f32 v37, v40, v41
	v_sub_f32_e32 v42, v42, v192
	v_sub_f32_e32 v43, v43, v192
	v_exp_f32_e32 v42, v42
	v_exp_f32_e32 v43, v43
	v_add_f32_e32 v194, v194, v42
	v_add_f32_e32 v195, v195, v43
	v_cvt_pk_bf16_f32 v42, v42, v43
	v_sub_f32_e32 v44, v44, v192
	v_sub_f32_e32 v45, v45, v192
	v_exp_f32_e32 v44, v44
	v_exp_f32_e32 v45, v45
	v_add_f32_e32 v196, v196, v44
	v_add_f32_e32 v197, v197, v45
	v_cvt_pk_bf16_f32 v43, v44, v45
	v_sub_f32_e32 v46, v46, v192
	v_sub_f32_e32 v47, v47, v192
	v_exp_f32_e32 v46, v46
	v_exp_f32_e32 v47, v47
	v_add_f32_e32 v194, v194, v46
	v_add_f32_e32 v195, v195, v47
	v_cvt_pk_bf16_f32 v44, v46, v47
	v_sub_f32_e32 v48, v48, v192
	v_sub_f32_e32 v49, v49, v192
	v_exp_f32_e32 v48, v48
	v_exp_f32_e32 v49, v49
	v_add_f32_e32 v196, v196, v48
	v_add_f32_e32 v197, v197, v49
	v_cvt_pk_bf16_f32 v45, v48, v49
	v_sub_f32_e32 v50, v50, v192
	v_sub_f32_e32 v51, v51, v192
	v_exp_f32_e32 v50, v50
	v_exp_f32_e32 v51, v51
	v_add_f32_e32 v194, v194, v50
	v_add_f32_e32 v195, v195, v51
	v_cvt_pk_bf16_f32 v50, v50, v51
	v_sub_f32_e32 v52, v52, v192
	v_sub_f32_e32 v53, v53, v192
	v_exp_f32_e32 v52, v52
	v_exp_f32_e32 v53, v53
	v_add_f32_e32 v196, v196, v52
	v_add_f32_e32 v197, v197, v53
	v_cvt_pk_bf16_f32 v51, v52, v53
	v_sub_f32_e32 v54, v54, v192
	v_sub_f32_e32 v55, v55, v192
	v_exp_f32_e32 v54, v54
	v_exp_f32_e32 v55, v55
	v_add_f32_e32 v194, v194, v54
	v_add_f32_e32 v195, v195, v55
	v_cvt_pk_bf16_f32 v52, v54, v55
	v_sub_f32_e32 v56, v56, v192
	v_sub_f32_e32 v57, v57, v192
	v_exp_f32_e32 v56, v56
	v_exp_f32_e32 v57, v57
	v_add_f32_e32 v196, v196, v56
	v_add_f32_e32 v197, v197, v57
	v_cvt_pk_bf16_f32 v53, v56, v57
	v_sub_f32_e32 v58, v58, v192
	v_sub_f32_e32 v59, v59, v192
	v_exp_f32_e32 v58, v58
	v_exp_f32_e32 v59, v59
	v_add_f32_e32 v194, v194, v58
	v_add_f32_e32 v195, v195, v59
	v_cvt_pk_bf16_f32 v58, v58, v59
	v_sub_f32_e32 v60, v60, v192
	v_sub_f32_e32 v61, v61, v192
	v_exp_f32_e32 v60, v60
	v_exp_f32_e32 v61, v61
	v_add_f32_e32 v196, v196, v60
	v_add_f32_e32 v197, v197, v61
	v_cvt_pk_bf16_f32 v59, v60, v61
	v_sub_f32_e32 v62, v62, v192
	v_sub_f32_e32 v63, v63, v192
	v_exp_f32_e32 v62, v62
	v_exp_f32_e32 v63, v63
	v_add_f32_e32 v194, v194, v62
	v_add_f32_e32 v195, v195, v63
	v_cvt_pk_bf16_f32 v60, v62, v63
	v_sub_f32_e32 v64, v64, v192
	v_sub_f32_e32 v65, v65, v192
	v_exp_f32_e32 v64, v64
	v_exp_f32_e32 v65, v65
	v_add_f32_e32 v196, v196, v64
	v_add_f32_e32 v197, v197, v65
	v_cvt_pk_bf16_f32 v61, v64, v65
	v_sub_f32_e32 v66, v66, v192
	v_sub_f32_e32 v67, v67, v192
	v_exp_f32_e32 v66, v66
	v_exp_f32_e32 v67, v67
	v_add_f32_e32 v194, v194, v66
	v_add_f32_e32 v195, v195, v67
	v_cvt_pk_bf16_f32 v66, v66, v67
	v_sub_f32_e32 v68, v68, v192
	v_sub_f32_e32 v69, v69, v192
	v_exp_f32_e32 v68, v68
	v_exp_f32_e32 v69, v69
	v_add_f32_e32 v196, v196, v68
	v_add_f32_e32 v197, v197, v69
	v_cvt_pk_bf16_f32 v67, v68, v69
	v_sub_f32_e32 v70, v70, v192
	v_sub_f32_e32 v71, v71, v192
	v_exp_f32_e32 v70, v70
	v_exp_f32_e32 v71, v71
	v_add_f32_e32 v194, v194, v70
	v_add_f32_e32 v195, v195, v71
	v_cvt_pk_bf16_f32 v68, v70, v71
	v_sub_f32_e32 v72, v72, v192
	v_sub_f32_e32 v73, v73, v192
	v_exp_f32_e32 v72, v72
	v_exp_f32_e32 v73, v73
	v_add_f32_e32 v196, v196, v72
	v_add_f32_e32 v197, v197, v73
	v_cvt_pk_bf16_f32 v69, v72, v73
	v_sub_f32_e32 v74, v74, v192
	v_sub_f32_e32 v75, v75, v192
	v_exp_f32_e32 v74, v74
	v_exp_f32_e32 v75, v75
	v_add_f32_e32 v194, v194, v74
	v_add_f32_e32 v195, v195, v75
	v_cvt_pk_bf16_f32 v74, v74, v75
	v_sub_f32_e32 v76, v76, v192
	v_sub_f32_e32 v77, v77, v192
	v_exp_f32_e32 v76, v76
	v_exp_f32_e32 v77, v77
	v_add_f32_e32 v196, v196, v76
	v_add_f32_e32 v197, v197, v77
	v_cvt_pk_bf16_f32 v75, v76, v77
	v_sub_f32_e32 v78, v78, v192
	v_sub_f32_e32 v79, v79, v192
	v_exp_f32_e32 v78, v78
	v_exp_f32_e32 v79, v79
	v_add_f32_e32 v194, v194, v78
	v_add_f32_e32 v195, v195, v79
	v_cvt_pk_bf16_f32 v76, v78, v79
	v_sub_f32_e32 v80, v80, v192
	v_sub_f32_e32 v81, v81, v192
	v_exp_f32_e32 v80, v80
	v_exp_f32_e32 v81, v81
	v_add_f32_e32 v196, v196, v80
	v_add_f32_e32 v197, v197, v81
	v_cvt_pk_bf16_f32 v77, v80, v81
	ds_read_b64_tr_b16 v[148:149], v184 offset:9216
	ds_read_b64_tr_b16 v[150:151], v184 offset:9792
	ds_read_b64_tr_b16 v[152:153], v184 offset:9280
	ds_read_b64_tr_b16 v[154:155], v184 offset:9856
	ds_read_b64_tr_b16 v[156:157], v184 offset:11520
	ds_read_b64_tr_b16 v[158:159], v184 offset:12096
	ds_read_b64_tr_b16 v[160:161], v184 offset:11584
	ds_read_b64_tr_b16 v[162:163], v184 offset:12160
	ds_read_b64_tr_b16 v[164:165], v184 offset:13824
	ds_read_b64_tr_b16 v[166:167], v184 offset:14400
	ds_read_b64_tr_b16 v[168:169], v184 offset:13888
	ds_read_b64_tr_b16 v[170:171], v184 offset:14464
	s_waitcnt lgkmcnt(10)
	v_mfma_f32_32x32x16_bf16 v[116:131], v[148:151], v[2:5], 0
	s_waitcnt lgkmcnt(8)
	v_mfma_f32_32x32x16_bf16 v[132:147], v[152:155], v[2:5], 0
	ds_read_b64_tr_b16 v[172:173], v184 offset:16128
	ds_read_b64_tr_b16 v[174:175], v184 offset:16704
	ds_read_b64_tr_b16 v[176:177], v184 offset:16192
	ds_read_b64_tr_b16 v[178:179], v184 offset:16768
	s_waitcnt lgkmcnt(10)
	v_mfma_f32_32x32x16_bf16 v[116:131], v[156:159], v[10:13], v[116:131]
	s_waitcnt lgkmcnt(8)
	v_mfma_f32_32x32x16_bf16 v[132:147], v[160:163], v[10:13], v[132:147]
	ds_read_b64_tr_b16 v[148:149], v184 offset:27648
	ds_read_b64_tr_b16 v[150:151], v184 offset:28224
	ds_read_b64_tr_b16 v[152:153], v184 offset:27712
	ds_read_b64_tr_b16 v[154:155], v184 offset:28288
	s_waitcnt lgkmcnt(10)
	v_mfma_f32_32x32x16_bf16 v[116:131], v[164:167], v[18:21], v[116:131]
	s_waitcnt lgkmcnt(8)
	v_mfma_f32_32x32x16_bf16 v[132:147], v[168:171], v[18:21], v[132:147]
	ds_read_b64_tr_b16 v[156:157], v184 offset:29952
	ds_read_b64_tr_b16 v[158:159], v184 offset:30528
	ds_read_b64_tr_b16 v[160:161], v184 offset:30016
	ds_read_b64_tr_b16 v[162:163], v184 offset:30592
	s_waitcnt lgkmcnt(10)
	v_mfma_f32_32x32x16_bf16 v[116:131], v[172:175], v[26:29], v[116:131]
	s_waitcnt lgkmcnt(8)
	v_mfma_f32_32x32x16_bf16 v[132:147], v[176:179], v[26:29], v[132:147]
	ds_read_b64_tr_b16 v[164:165], v184 offset:32256
	ds_read_b64_tr_b16 v[166:167], v184 offset:32832
	ds_read_b64_tr_b16 v[168:169], v184 offset:32320
	ds_read_b64_tr_b16 v[170:171], v184 offset:32896
	s_waitcnt lgkmcnt(10)
	v_mfma_f32_32x32x16_bf16 v[116:131], v[148:151], v[34:37], v[116:131]
	s_waitcnt lgkmcnt(8)
	v_mfma_f32_32x32x16_bf16 v[132:147], v[152:155], v[34:37], v[132:147]
	ds_read_b64_tr_b16 v[172:173], v184 offset:34560
	ds_read_b64_tr_b16 v[174:175], v184 offset:35136
	ds_read_b64_tr_b16 v[176:177], v184 offset:34624
	ds_read_b64_tr_b16 v[178:179], v184 offset:35200
	s_waitcnt lgkmcnt(10)
	v_mfma_f32_32x32x16_bf16 v[116:131], v[156:159], v[42:45], v[116:131]
	s_waitcnt lgkmcnt(8)
	v_mfma_f32_32x32x16_bf16 v[132:147], v[160:163], v[42:45], v[132:147]
	ds_read_b64_tr_b16 v[148:149], v184 offset:46080
	ds_read_b64_tr_b16 v[150:151], v184 offset:46656
	ds_read_b64_tr_b16 v[152:153], v184 offset:46144
	ds_read_b64_tr_b16 v[154:155], v184 offset:46720
	s_waitcnt lgkmcnt(10)
	v_mfma_f32_32x32x16_bf16 v[116:131], v[164:167], v[50:53], v[116:131]
	s_waitcnt lgkmcnt(8)
	v_mfma_f32_32x32x16_bf16 v[132:147], v[168:171], v[50:53], v[132:147]
	ds_read_b64_tr_b16 v[156:157], v184 offset:48384
	ds_read_b64_tr_b16 v[158:159], v184 offset:48960
	ds_read_b64_tr_b16 v[160:161], v184 offset:48448
	ds_read_b64_tr_b16 v[162:163], v184 offset:49024
	s_waitcnt lgkmcnt(10)
	v_mfma_f32_32x32x16_bf16 v[116:131], v[172:175], v[58:61], v[116:131]
	s_waitcnt lgkmcnt(8)
	v_mfma_f32_32x32x16_bf16 v[132:147], v[176:179], v[58:61], v[132:147]
	s_waitcnt lgkmcnt(6)
	v_mfma_f32_32x32x16_bf16 v[116:131], v[148:151], v[66:69], v[116:131]
	s_waitcnt lgkmcnt(4)
	v_mfma_f32_32x32x16_bf16 v[132:147], v[152:155], v[66:69], v[132:147]
	s_waitcnt lgkmcnt(2)
	v_mfma_f32_32x32x16_bf16 v[116:131], v[156:159], v[74:77], v[116:131]
	s_waitcnt lgkmcnt(0)
	v_mfma_f32_32x32x16_bf16 v[132:147], v[160:163], v[74:77], v[132:147]
	s_branch .Lmb_fin
.Lmb_odd:
	ds_read_b128 v[148:151], v183 offset:4608
	ds_read_b128 v[152:155], v183 offset:4640
	ds_read_b128 v[156:159], v183 offset:4672
	ds_read_b128 v[160:163], v183 offset:4704
	ds_read_b128 v[164:167], v183 offset:18432
	ds_read_b128 v[168:171], v183 offset:18464
	ds_read_b128 v[172:175], v183 offset:18496
	ds_read_b128 v[176:179], v183 offset:18528
	s_waitcnt lgkmcnt(7)
	v_mfma_f32_32x32x16_bf16 v[2:17], v[148:151], v[100:103], 0
	s_waitcnt lgkmcnt(6)
	v_mfma_f32_32x32x16_bf16 v[2:17], v[152:155], v[104:107], v[2:17]
	s_waitcnt lgkmcnt(5)
	v_mfma_f32_32x32x16_bf16 v[2:17], v[156:159], v[108:111], v[2:17]
	s_waitcnt lgkmcnt(4)
	v_mfma_f32_32x32x16_bf16 v[2:17], v[160:163], v[112:115], v[2:17]
	ds_read_b128 v[148:151], v183 offset:23040
	ds_read_b128 v[152:155], v183 offset:23072
	ds_read_b128 v[156:159], v183 offset:23104
	ds_read_b128 v[160:163], v183 offset:23136
	s_waitcnt lgkmcnt(7)
	v_mfma_f32_32x32x16_bf16 v[18:33], v[164:167], v[100:103], 0
	s_waitcnt lgkmcnt(6)
	v_mfma_f32_32x32x16_bf16 v[18:33], v[168:171], v[104:107], v[18:33]
	s_waitcnt lgkmcnt(5)
	v_mfma_f32_32x32x16_bf16 v[18:33], v[172:175], v[108:111], v[18:33]
	s_waitcnt lgkmcnt(4)
	v_mfma_f32_32x32x16_bf16 v[18:33], v[176:179], v[112:115], v[18:33]
	ds_read_b128 v[164:167], v183 offset:36864
	ds_read_b128 v[168:171], v183 offset:36896
	ds_read_b128 v[172:175], v183 offset:36928
	ds_read_b128 v[176:179], v183 offset:36960
	s_waitcnt lgkmcnt(7)
	v_mfma_f32_32x32x16_bf16 v[34:49], v[148:151], v[100:103], 0
	s_waitcnt lgkmcnt(6)
	v_mfma_f32_32x32x16_bf16 v[34:49], v[152:155], v[104:107], v[34:49]
	s_waitcnt lgkmcnt(5)
	v_mfma_f32_32x32x16_bf16 v[34:49], v[156:159], v[108:111], v[34:49]
	s_waitcnt lgkmcnt(4)
	v_mfma_f32_32x32x16_bf16 v[34:49], v[160:163], v[112:115], v[34:49]
	ds_read_b128 v[148:151], v183 offset:41472
	ds_read_b128 v[152:155], v183 offset:41504
	ds_read_b128 v[156:159], v183 offset:41536
	ds_read_b128 v[160:163], v183 offset:41568
	s_waitcnt lgkmcnt(7)
	v_mfma_f32_32x32x16_bf16 v[50:65], v[164:167], v[100:103], 0
	s_waitcnt lgkmcnt(6)
	v_mfma_f32_32x32x16_bf16 v[50:65], v[168:171], v[104:107], v[50:65]
	s_waitcnt lgkmcnt(5)
	v_mfma_f32_32x32x16_bf16 v[50:65], v[172:175], v[108:111], v[50:65]
	s_waitcnt lgkmcnt(4)
	v_mfma_f32_32x32x16_bf16 v[50:65], v[176:179], v[112:115], v[50:65]
	s_waitcnt lgkmcnt(3)
	v_mfma_f32_32x32x16_bf16 v[66:81], v[148:151], v[100:103], 0
	s_waitcnt lgkmcnt(2)
	v_mfma_f32_32x32x16_bf16 v[66:81], v[152:155], v[104:107], v[66:81]
	s_waitcnt lgkmcnt(1)
	v_mfma_f32_32x32x16_bf16 v[66:81], v[156:159], v[108:111], v[66:81]
	s_waitcnt lgkmcnt(0)
	v_mfma_f32_32x32x16_bf16 v[66:81], v[160:163], v[112:115], v[66:81]
	s_add_i32 s33, s21, 1
	s_cmp_le_u32 s20, 1
	s_cbranch_scc1 .Lmb_nopf1
	s_cmpk_gt_i32 s33, 0x5ff
	s_cbranch_scc1 .Lmb_nopf1
	s_and_b32 s25, s33, 63
	s_lshr_b32 s26, s33, 6
	s_and_b32 s11, s26, 3
	s_lshr_b32 s27, s26, 2
	s_cmp_ge_u32 s27, 3
	s_cselect_b32 s12, 1, 0
	s_mul_i32 s10, s12, 3
	s_sub_i32 s10, s27, s10
	s_lshl_b32 s6, s10, 1
	s_sub_i32 s13, 6, s6
	s_lshr_b32 s7, s25, s13
	s_lshl_b32 s8, 1, s13
	s_add_i32 s8, s8, -1
	s_and_b32 s8, s25, s8
	s_lshl_b32 s8, s8, 8
	s_lshr_b32 s9, 0x4000, s6
	s_add_i32 s15, s9, -1
	s_mul_i32 s28, s12, 0x6000000
	s_add_u32 s4, s94, 0x7800000
	s_addc_u32 s5, s95, 0
	s_add_u32 s4, s4, s28
	s_addc_u32 s5, s5, 0
	s_lshl_b32 s22, s10, 9
	s_lshl_b32 s23, s11, 7
	s_add_i32 s22, s22, s23
	s_add_i32 s22, s22, 0x600
	s_add_i32 s23, s22, 0x600
	s_add_i32 s24, s22, 0xc00
	s_add_u32 s34, s4, s23
	s_addc_u32 s35, s5, 0
	s_add_u32 s36, s4, s24
	s_addc_u32 s37, s5, 0
	s_add_i32 s26, s8, -64
	s_lshl_b32 s25, s31, 5
	s_add_i32 s25, s25, s8
	v_add_u32_e32 v189, s25, v180
	v_lshlrev_b32_e32 v189, s6, v189
	v_add_u32_e32 v189, s7, v189
	v_mul_u32_u24_e32 v190, 0x1800, v189
	v_lshl_add_u32 v190, v181, 4, v190
	v_add_u32_e32 v190, s22, v190
	global_load_dwordx4 v[100:103], v190, s[4:5]
	global_load_dwordx4 v[104:107], v190, s[4:5] offset:32
	global_load_dwordx4 v[108:111], v190, s[4:5] offset:64
	global_load_dwordx4 v[112:115], v190, s[4:5] offset:96
	v_add_u32_e32 v200, s26, v187
	v_med3_i32 v200, v200, 0, s15
	v_lshlrev_b32_e32 v200, s6, v200
	v_add_u32_e32 v200, s7, v200
	v_mul_u32_u24_e32 v200, 0x1800, v200
	v_add_u32_e32 v200, v200, v188
	global_load_dwordx4 v[82:85], v200, s[34:35]
	global_load_dwordx4 v[86:89], v200, s[36:37]
	v_add_u32_e32 v201, s26, v187
	v_add_u32_e32 v201, 64, v201
	v_med3_i32 v201, v201, 0, s15
	v_lshlrev_b32_e32 v201, s6, v201
	v_add_u32_e32 v201, s7, v201
	v_mul_u32_u24_e32 v201, 0x1800, v201
	v_add_u32_e32 v201, v201, v188
	global_load_dwordx4 v[90:93], v201, s[34:35]
	global_load_dwordx4 v[94:97], v201, s[36:37]
	v_add_u32_e32 v202, s26, v187
	v_add_u32_e32 v202, 128, v202
	v_med3_i32 v202, v202, 0, s15
	v_lshlrev_b32_e32 v202, s6, v202
	v_add_u32_e32 v202, s7, v202
	v_mul_u32_u24_e32 v202, 0x1800, v202
	v_add_u32_e32 v202, v202, v188
	global_load_dwordx4 v[214:217], v202, s[34:35]
	global_load_dwordx4 v[218:221], v202, s[36:37]
	v_add_u32_e32 v203, s26, v187
	v_add_u32_e32 v203, 192, v203
	v_med3_i32 v203, v203, 0, s15
	v_lshlrev_b32_e32 v203, s6, v203
	v_add_u32_e32 v203, s7, v203
	v_mul_u32_u24_e32 v203, 0x1800, v203
	v_add_u32_e32 v203, v203, v188
	global_load_dwordx4 v[222:225], v203, s[34:35]
	global_load_dwordx4 v[226:229], v203, s[36:37]
	v_add_u32_e32 v204, s26, v187
	v_add_u32_e32 v204, 256, v204
	v_med3_i32 v204, v204, 0, s15
	v_lshlrev_b32_e32 v204, s6, v204
	v_add_u32_e32 v204, s7, v204
	v_mul_u32_u24_e32 v204, 0x1800, v204
	v_add_u32_e32 v204, v204, v188
	global_load_dwordx4 v[234:237], v204, s[34:35]
	global_load_dwordx4 v[238:241], v204, s[36:37]
	v_add_u32_e32 v205, s26, v187
	v_add_u32_e32 v205, 320, v205
	v_med3_i32 v205, v205, 0, s15
	v_lshlrev_b32_e32 v205, s6, v205
	v_add_u32_e32 v205, s7, v205
	v_mul_u32_u24_e32 v205, 0x1800, v205
	v_add_u32_e32 v205, v205, v188
	global_load_dwordx4 v[242:245], v205, s[34:35]
	global_load_dwordx4 v[246:249], v205, s[36:37]
.Lmb_nopf1:
	s_cmp_lg_u32 s50, 0
	s_cbranch_scc1 .Lmb_tv1_0
	s_nop 7
	s_nop 7
	v_mov_b32_e32 v2, v198
	v_mov_b32_e32 v3, v198
	v_mov_b32_e32 v4, v198
	v_mov_b32_e32 v5, v198
	v_mov_b32_e32 v6, v198
	v_mov_b32_e32 v7, v198
	v_mov_b32_e32 v8, v198
	v_mov_b32_e32 v9, v198
	v_mov_b32_e32 v10, v198
	v_mov_b32_e32 v11, v198
	v_mov_b32_e32 v12, v198
	v_mov_b32_e32 v13, v198
	v_mov_b32_e32 v14, v198
	v_mov_b32_e32 v15, v198
	v_mov_b32_e32 v16, v198
	v_mov_b32_e32 v17, v198
.Lmb_tv1_0:
	s_cmp_lg_u32 s51, 0
	s_cbranch_scc1 .Lmb_tv1_1
	s_nop 7
	s_nop 7
	v_mov_b32_e32 v18, v198
	v_mov_b32_e32 v19, v198
	v_mov_b32_e32 v20, v198
	v_mov_b32_e32 v21, v198
	v_mov_b32_e32 v22, v198
	v_mov_b32_e32 v23, v198
	v_mov_b32_e32 v24, v198
	v_mov_b32_e32 v25, v198
	v_mov_b32_e32 v26, v198
	v_mov_b32_e32 v27, v198
	v_mov_b32_e32 v28, v198
	v_mov_b32_e32 v29, v198
	v_mov_b32_e32 v30, v198
	v_mov_b32_e32 v31, v198
	v_mov_b32_e32 v32, v198
	v_mov_b32_e32 v33, v198
	v_mov_b32_e32 v34, v198
	v_mov_b32_e32 v35, v198
	v_mov_b32_e32 v36, v198
	v_mov_b32_e32 v37, v198
	v_mov_b32_e32 v38, v198
	v_mov_b32_e32 v39, v198
	v_mov_b32_e32 v40, v198
	v_mov_b32_e32 v41, v198
	v_mov_b32_e32 v42, v198
	v_mov_b32_e32 v43, v198
	v_mov_b32_e32 v44, v198
	v_mov_b32_e32 v45, v198
	v_mov_b32_e32 v46, v198
	v_mov_b32_e32 v47, v198
	v_mov_b32_e32 v48, v198
	v_mov_b32_e32 v49, v198
.Lmb_tv1_1:
	s_cmp_lg_u32 s52, 0
	s_cbranch_scc1 .Lmb_tv1_2
	s_nop 7
	s_nop 7
	v_mov_b32_e32 v50, v198
	v_mov_b32_e32 v51, v198
	v_mov_b32_e32 v52, v198
	v_mov_b32_e32 v53, v198
	v_mov_b32_e32 v54, v198
	v_mov_b32_e32 v55, v198
	v_mov_b32_e32 v56, v198
	v_mov_b32_e32 v57, v198
	v_mov_b32_e32 v58, v198
	v_mov_b32_e32 v59, v198
	v_mov_b32_e32 v60, v198
	v_mov_b32_e32 v61, v198
	v_mov_b32_e32 v62, v198
	v_mov_b32_e32 v63, v198
	v_mov_b32_e32 v64, v198
	v_mov_b32_e32 v65, v198
	v_mov_b32_e32 v66, v198
	v_mov_b32_e32 v67, v198
	v_mov_b32_e32 v68, v198
	v_mov_b32_e32 v69, v198
	v_mov_b32_e32 v70, v198
	v_mov_b32_e32 v71, v198
	v_mov_b32_e32 v72, v198
	v_mov_b32_e32 v73, v198
	v_mov_b32_e32 v74, v198
	v_mov_b32_e32 v75, v198
	v_mov_b32_e32 v76, v198
	v_mov_b32_e32 v77, v198
	v_mov_b32_e32 v78, v198
	v_mov_b32_e32 v79, v198
	v_mov_b32_e32 v80, v198
	v_mov_b32_e32 v81, v198
.Lmb_tv1_2:
	s_nop 7
	s_nop 4
	v_cmp_ge_i32_e64 s[40:41], 32, v186
	v_cmp_ge_i32_e64 s[42:43], 33, v186
	v_cmp_ge_i32_e64 s[44:45], 34, v186
	v_cmp_ge_i32_e64 s[46:47], 35, v186
	v_cndmask_b32_e64 v2, v198, v2, s[40:41]
	v_cndmask_b32_e64 v3, v198, v3, s[42:43]
	v_cndmask_b32_e64 v4, v198, v4, s[44:45]
	v_cndmask_b32_e64 v5, v198, v5, s[46:47]
	v_cmp_ge_i32_e64 s[40:41], 36, v186
	v_cmp_ge_i32_e64 s[42:43], 37, v186
	v_cmp_ge_i32_e64 s[44:45], 38, v186
	v_cmp_ge_i32_e64 s[46:47], 39, v186
	v_cndmask_b32_e64 v6, v198, v6, s[40:41]
	v_cndmask_b32_e64 v7, v198, v7, s[42:43]
	v_cndmask_b32_e64 v8, v198, v8, s[44:45]
	v_cndmask_b32_e64 v9, v198, v9, s[46:47]
	v_cmp_ge_i32_e64 s[40:41], 48, v186
	v_cmp_ge_i32_e64 s[42:43], 49, v186
	v_cmp_ge_i32_e64 s[44:45], 50, v186
	v_cmp_ge_i32_e64 s[46:47], 51, v186
	v_cndmask_b32_e64 v10, v198, v10, s[40:41]
	v_cndmask_b32_e64 v11, v198, v11, s[42:43]
	v_cndmask_b32_e64 v12, v198, v12, s[44:45]
	v_cndmask_b32_e64 v13, v198, v13, s[46:47]
	v_cmp_ge_i32_e64 s[40:41], 52, v186
	v_cmp_ge_i32_e64 s[42:43], 53, v186
	v_cmp_ge_i32_e64 s[44:45], 54, v186
	v_cmp_ge_i32_e64 s[46:47], 55, v186
	v_cndmask_b32_e64 v14, v198, v14, s[40:41]
	v_cndmask_b32_e64 v15, v198, v15, s[42:43]
	v_cndmask_b32_e64 v16, v198, v16, s[44:45]
	v_cndmask_b32_e64 v17, v198, v17, s[46:47]
	v_cmp_le_i32_e64 s[40:41], 32, v186
	v_cmp_le_i32_e64 s[42:43], 33, v186
	v_cmp_le_i32_e64 s[44:45], 34, v186
	v_cmp_le_i32_e64 s[46:47], 35, v186
	v_cndmask_b32_e64 v66, v198, v66, s[40:41]
	v_cndmask_b32_e64 v67, v198, v67, s[42:43]
	v_cndmask_b32_e64 v68, v198, v68, s[44:45]
	v_cndmask_b32_e64 v69, v198, v69, s[46:47]
	v_cmp_le_i32_e64 s[40:41], 36, v186
	v_cmp_le_i32_e64 s[42:43], 37, v186
	v_cmp_le_i32_e64 s[44:45], 38, v186
	v_cmp_le_i32_e64 s[46:47], 39, v186
	v_cndmask_b32_e64 v70, v198, v70, s[40:41]
	v_cndmask_b32_e64 v71, v198, v71, s[42:43]
	v_cndmask_b32_e64 v72, v198, v72, s[44:45]
	v_cndmask_b32_e64 v73, v198, v73, s[46:47]
	v_cmp_le_i32_e64 s[40:41], 48, v186
	v_cmp_le_i32_e64 s[42:43], 49, v186
	v_cmp_le_i32_e64 s[44:45], 50, v186
	v_cmp_le_i32_e64 s[46:47], 51, v186
	v_cndmask_b32_e64 v74, v198, v74, s[40:41]
	v_cndmask_b32_e64 v75, v198, v75, s[42:43]
	v_cndmask_b32_e64 v76, v198, v76, s[44:45]
	v_cndmask_b32_e64 v77, v198, v77, s[46:47]
	v_cmp_le_i32_e64 s[40:41], 52, v186
	v_cmp_le_i32_e64 s[42:43], 53, v186
	v_cmp_le_i32_e64 s[44:45], 54, v186
	v_cmp_le_i32_e64 s[46:47], 55, v186
	v_cndmask_b32_e64 v78, v198, v78, s[40:41]
	v_cndmask_b32_e64 v79, v198, v79, s[42:43]
	v_cndmask_b32_e64 v80, v198, v80, s[44:45]
	v_cndmask_b32_e64 v81, v198, v81, s[46:47]
	v_max3_f32 v192, v2, v3, v4
	v_max3_f32 v193, v5, v6, v7
	v_max3_f32 v192, v192, v8, v9
	v_max3_f32 v193, v193, v10, v11
	v_max3_f32 v192, v192, v12, v13
	v_max3_f32 v193, v193, v14, v15
	v_max3_f32 v192, v192, v16, v17
	v_max3_f32 v193, v193, v18, v19
	v_max3_f32 v192, v192, v20, v21
	v_max3_f32 v193, v193, v22, v23
	v_max3_f32 v192, v192, v24, v25
	v_max3_f32 v193, v193, v26, v27
	v_max3_f32 v192, v192, v28, v29
	v_max3_f32 v193, v193, v30, v31
	v_max3_f32 v192, v192, v32, v33
	v_max3_f32 v193, v193, v34, v35
	v_max3_f32 v192, v192, v36, v37
	v_max3_f32 v193, v193, v38, v39
	v_max3_f32 v192, v192, v40, v41
	v_max3_f32 v193, v193, v42, v43
	v_max3_f32 v192, v192, v44, v45
	v_max3_f32 v193, v193, v46, v47
	v_max3_f32 v192, v192, v48, v49
	v_max3_f32 v193, v193, v50, v51
	v_max3_f32 v192, v192, v52, v53
	v_max3_f32 v193, v193, v54, v55
	v_max3_f32 v192, v192, v56, v57
	v_max3_f32 v193, v193, v58, v59
	v_max3_f32 v192, v192, v60, v61
	v_max3_f32 v193, v193, v62, v63
	v_max3_f32 v192, v192, v64, v65
	v_max3_f32 v193, v193, v66, v67
	v_max3_f32 v192, v192, v68, v69
	v_max3_f32 v193, v193, v70, v71
	v_max3_f32 v192, v192, v72, v73
	v_max3_f32 v193, v193, v74, v75
	v_max3_f32 v192, v192, v76, v77
	v_max3_f32 v193, v193, v78, v79
	v_max3_f32 v192, v192, v80, v81
	v_max_f32_e32 v192, v192, v193
	v_mov_b32_e32 v193, v192
	s_nop 1
	v_permlane32_swap_b32_e32 v192, v193
	v_max_f32_e32 v192, v192, v193
	v_mov_b32_e32 v194, 0
	v_mov_b32_e32 v195, 0
	v_mov_b32_e32 v196, 0
	v_mov_b32_e32 v197, 0
	v_sub_f32_e32 v2, v2, v192
	v_sub_f32_e32 v3, v3, v192
	v_exp_f32_e32 v2, v2
	v_exp_f32_e32 v3, v3
	v_add_f32_e32 v194, v194, v2
	v_add_f32_e32 v195, v195, v3
	v_cvt_pk_bf16_f32 v2, v2, v3
	v_sub_f32_e32 v4, v4, v192
	v_sub_f32_e32 v5, v5, v192
	v_exp_f32_e32 v4, v4
	v_exp_f32_e32 v5, v5
	v_add_f32_e32 v196, v196, v4
	v_add_f32_e32 v197, v197, v5
	v_cvt_pk_bf16_f32 v3, v4, v5
	v_sub_f32_e32 v6, v6, v192
	v_sub_f32_e32 v7, v7, v192
	v_exp_f32_e32 v6, v6
	v_exp_f32_e32 v7, v7
	v_add_f32_e32 v194, v194, v6
	v_add_f32_e32 v195, v195, v7
	v_cvt_pk_bf16_f32 v4, v6, v7
	v_sub_f32_e32 v8, v8, v192
	v_sub_f32_e32 v9, v9, v192
	v_exp_f32_e32 v8, v8
	v_exp_f32_e32 v9, v9
	v_add_f32_e32 v196, v196, v8
	v_add_f32_e32 v197, v197, v9
	v_cvt_pk_bf16_f32 v5, v8, v9
	v_sub_f32_e32 v10, v10, v192
	v_sub_f32_e32 v11, v11, v192
	v_exp_f32_e32 v10, v10
	v_exp_f32_e32 v11, v11
	v_add_f32_e32 v194, v194, v10
	v_add_f32_e32 v195, v195, v11
	v_cvt_pk_bf16_f32 v10, v10, v11
	v_sub_f32_e32 v12, v12, v192
	v_sub_f32_e32 v13, v13, v192
	v_exp_f32_e32 v12, v12
	v_exp_f32_e32 v13, v13
	v_add_f32_e32 v196, v196, v12
	v_add_f32_e32 v197, v197, v13
	v_cvt_pk_bf16_f32 v11, v12, v13
	v_sub_f32_e32 v14, v14, v192
	v_sub_f32_e32 v15, v15, v192
	v_exp_f32_e32 v14, v14
	v_exp_f32_e32 v15, v15
	v_add_f32_e32 v194, v194, v14
	v_add_f32_e32 v195, v195, v15
	v_cvt_pk_bf16_f32 v12, v14, v15
	v_sub_f32_e32 v16, v16, v192
	v_sub_f32_e32 v17, v17, v192
	v_exp_f32_e32 v16, v16
	v_exp_f32_e32 v17, v17
	v_add_f32_e32 v196, v196, v16
	v_add_f32_e32 v197, v197, v17
	v_cvt_pk_bf16_f32 v13, v16, v17
	v_sub_f32_e32 v18, v18, v192
	v_sub_f32_e32 v19, v19, v192
	v_exp_f32_e32 v18, v18
	v_exp_f32_e32 v19, v19
	v_add_f32_e32 v194, v194, v18
	v_add_f32_e32 v195, v195, v19
	v_cvt_pk_bf16_f32 v18, v18, v19
	v_sub_f32_e32 v20, v20, v192
	v_sub_f32_e32 v21, v21, v192
	v_exp_f32_e32 v20, v20
	v_exp_f32_e32 v21, v21
	v_add_f32_e32 v196, v196, v20
	v_add_f32_e32 v197, v197, v21
	v_cvt_pk_bf16_f32 v19, v20, v21
	v_sub_f32_e32 v22, v22, v192
	v_sub_f32_e32 v23, v23, v192
	v_exp_f32_e32 v22, v22
	v_exp_f32_e32 v23, v23
	v_add_f32_e32 v194, v194, v22
	v_add_f32_e32 v195, v195, v23
	v_cvt_pk_bf16_f32 v20, v22, v23
	v_sub_f32_e32 v24, v24, v192
	v_sub_f32_e32 v25, v25, v192
	v_exp_f32_e32 v24, v24
	v_exp_f32_e32 v25, v25
	v_add_f32_e32 v196, v196, v24
	v_add_f32_e32 v197, v197, v25
	v_cvt_pk_bf16_f32 v21, v24, v25
	v_sub_f32_e32 v26, v26, v192
	v_sub_f32_e32 v27, v27, v192
	v_exp_f32_e32 v26, v26
	v_exp_f32_e32 v27, v27
	v_add_f32_e32 v194, v194, v26
	v_add_f32_e32 v195, v195, v27
	v_cvt_pk_bf16_f32 v26, v26, v27
	v_sub_f32_e32 v28, v28, v192
	v_sub_f32_e32 v29, v29, v192
	v_exp_f32_e32 v28, v28
	v_exp_f32_e32 v29, v29
	v_add_f32_e32 v196, v196, v28
	v_add_f32_e32 v197, v197, v29
	v_cvt_pk_bf16_f32 v27, v28, v29
	v_sub_f32_e32 v30, v30, v192
	v_sub_f32_e32 v31, v31, v192
	v_exp_f32_e32 v30, v30
	v_exp_f32_e32 v31, v31
	v_add_f32_e32 v194, v194, v30
	v_add_f32_e32 v195, v195, v31
	v_cvt_pk_bf16_f32 v28, v30, v31
	v_sub_f32_e32 v32, v32, v192
	v_sub_f32_e32 v33, v33, v192
	v_exp_f32_e32 v32, v32
	v_exp_f32_e32 v33, v33
	v_add_f32_e32 v196, v196, v32
	v_add_f32_e32 v197, v197, v33
	v_cvt_pk_bf16_f32 v29, v32, v33
	v_sub_f32_e32 v34, v34, v192
	v_sub_f32_e32 v35, v35, v192
	v_exp_f32_e32 v34, v34
	v_exp_f32_e32 v35, v35
	v_add_f32_e32 v194, v194, v34
	v_add_f32_e32 v195, v195, v35
	v_cvt_pk_bf16_f32 v34, v34, v35
	v_sub_f32_e32 v36, v36, v192
	v_sub_f32_e32 v37, v37, v192
	v_exp_f32_e32 v36, v36
	v_exp_f32_e32 v37, v37
	v_add_f32_e32 v196, v196, v36
	v_add_f32_e32 v197, v197, v37
	v_cvt_pk_bf16_f32 v35, v36, v37
	v_sub_f32_e32 v38, v38, v192
	v_sub_f32_e32 v39, v39, v192
	v_exp_f32_e32 v38, v38
	v_exp_f32_e32 v39, v39
	v_add_f32_e32 v194, v194, v38
	v_add_f32_e32 v195, v195, v39
	v_cvt_pk_bf16_f32 v36, v38, v39
	v_sub_f32_e32 v40, v40, v192
	v_sub_f32_e32 v41, v41, v192
	v_exp_f32_e32 v40, v40
	v_exp_f32_e32 v41, v41
	v_add_f32_e32 v196, v196, v40
	v_add_f32_e32 v197, v197, v41
	v_cvt_pk_bf16_f32 v37, v40, v41
	v_sub_f32_e32 v42, v42, v192
	v_sub_f32_e32 v43, v43, v192
	v_exp_f32_e32 v42, v42
	v_exp_f32_e32 v43, v43
	v_add_f32_e32 v194, v194, v42
	v_add_f32_e32 v195, v195, v43
	v_cvt_pk_bf16_f32 v42, v42, v43
	v_sub_f32_e32 v44, v44, v192
	v_sub_f32_e32 v45, v45, v192
	v_exp_f32_e32 v44, v44
	v_exp_f32_e32 v45, v45
	v_add_f32_e32 v196, v196, v44
	v_add_f32_e32 v197, v197, v45
	v_cvt_pk_bf16_f32 v43, v44, v45
	v_sub_f32_e32 v46, v46, v192
	v_sub_f32_e32 v47, v47, v192
	v_exp_f32_e32 v46, v46
	v_exp_f32_e32 v47, v47
	v_add_f32_e32 v194, v194, v46
	v_add_f32_e32 v195, v195, v47
	v_cvt_pk_bf16_f32 v44, v46, v47
	v_sub_f32_e32 v48, v48, v192
	v_sub_f32_e32 v49, v49, v192
	v_exp_f32_e32 v48, v48
	v_exp_f32_e32 v49, v49
	v_add_f32_e32 v196, v196, v48
	v_add_f32_e32 v197, v197, v49
	v_cvt_pk_bf16_f32 v45, v48, v49
	v_sub_f32_e32 v50, v50, v192
	v_sub_f32_e32 v51, v51, v192
	v_exp_f32_e32 v50, v50
	v_exp_f32_e32 v51, v51
	v_add_f32_e32 v194, v194, v50
	v_add_f32_e32 v195, v195, v51
	v_cvt_pk_bf16_f32 v50, v50, v51
	v_sub_f32_e32 v52, v52, v192
	v_sub_f32_e32 v53, v53, v192
	v_exp_f32_e32 v52, v52
	v_exp_f32_e32 v53, v53
	v_add_f32_e32 v196, v196, v52
	v_add_f32_e32 v197, v197, v53
	v_cvt_pk_bf16_f32 v51, v52, v53
	v_sub_f32_e32 v54, v54, v192
	v_sub_f32_e32 v55, v55, v192
	v_exp_f32_e32 v54, v54
	v_exp_f32_e32 v55, v55
	v_add_f32_e32 v194, v194, v54
	v_add_f32_e32 v195, v195, v55
	v_cvt_pk_bf16_f32 v52, v54, v55
	v_sub_f32_e32 v56, v56, v192
	v_sub_f32_e32 v57, v57, v192
	v_exp_f32_e32 v56, v56
	v_exp_f32_e32 v57, v57
	v_add_f32_e32 v196, v196, v56
	v_add_f32_e32 v197, v197, v57
	v_cvt_pk_bf16_f32 v53, v56, v57
	v_sub_f32_e32 v58, v58, v192
	v_sub_f32_e32 v59, v59, v192
	v_exp_f32_e32 v58, v58
	v_exp_f32_e32 v59, v59
	v_add_f32_e32 v194, v194, v58
	v_add_f32_e32 v195, v195, v59
	v_cvt_pk_bf16_f32 v58, v58, v59
	v_sub_f32_e32 v60, v60, v192
	v_sub_f32_e32 v61, v61, v192
	v_exp_f32_e32 v60, v60
	v_exp_f32_e32 v61, v61
	v_add_f32_e32 v196, v196, v60
	v_add_f32_e32 v197, v197, v61
	v_cvt_pk_bf16_f32 v59, v60, v61
	v_sub_f32_e32 v62, v62, v192
	v_sub_f32_e32 v63, v63, v192
	v_exp_f32_e32 v62, v62
	v_exp_f32_e32 v63, v63
	v_add_f32_e32 v194, v194, v62
	v_add_f32_e32 v195, v195, v63
	v_cvt_pk_bf16_f32 v60, v62, v63
	v_sub_f32_e32 v64, v64, v192
	v_sub_f32_e32 v65, v65, v192
	v_exp_f32_e32 v64, v64
	v_exp_f32_e32 v65, v65
	v_add_f32_e32 v196, v196, v64
	v_add_f32_e32 v197, v197, v65
	v_cvt_pk_bf16_f32 v61, v64, v65
	v_sub_f32_e32 v66, v66, v192
	v_sub_f32_e32 v67, v67, v192
	v_exp_f32_e32 v66, v66
	v_exp_f32_e32 v67, v67
	v_add_f32_e32 v194, v194, v66
	v_add_f32_e32 v195, v195, v67
	v_cvt_pk_bf16_f32 v66, v66, v67
	v_sub_f32_e32 v68, v68, v192
	v_sub_f32_e32 v69, v69, v192
	v_exp_f32_e32 v68, v68
	v_exp_f32_e32 v69, v69
	v_add_f32_e32 v196, v196, v68
	v_add_f32_e32 v197, v197, v69
	v_cvt_pk_bf16_f32 v67, v68, v69
	v_sub_f32_e32 v70, v70, v192
	v_sub_f32_e32 v71, v71, v192
	v_exp_f32_e32 v70, v70
	v_exp_f32_e32 v71, v71
	v_add_f32_e32 v194, v194, v70
	v_add_f32_e32 v195, v195, v71
	v_cvt_pk_bf16_f32 v68, v70, v71
	v_sub_f32_e32 v72, v72, v192
	v_sub_f32_e32 v73, v73, v192
	v_exp_f32_e32 v72, v72
	v_exp_f32_e32 v73, v73
	v_add_f32_e32 v196, v196, v72
	v_add_f32_e32 v197, v197, v73
	v_cvt_pk_bf16_f32 v69, v72, v73
	v_sub_f32_e32 v74, v74, v192
	v_sub_f32_e32 v75, v75, v192
	v_exp_f32_e32 v74, v74
	v_exp_f32_e32 v75, v75
	v_add_f32_e32 v194, v194, v74
	v_add_f32_e32 v195, v195, v75
	v_cvt_pk_bf16_f32 v74, v74, v75
	v_sub_f32_e32 v76, v76, v192
	v_sub_f32_e32 v77, v77, v192
	v_exp_f32_e32 v76, v76
	v_exp_f32_e32 v77, v77
	v_add_f32_e32 v196, v196, v76
	v_add_f32_e32 v197, v197, v77
	v_cvt_pk_bf16_f32 v75, v76, v77
	v_sub_f32_e32 v78, v78, v192
	v_sub_f32_e32 v79, v79, v192
	v_exp_f32_e32 v78, v78
	v_exp_f32_e32 v79, v79
	v_add_f32_e32 v194, v194, v78
	v_add_f32_e32 v195, v195, v79
	v_cvt_pk_bf16_f32 v76, v78, v79
	v_sub_f32_e32 v80, v80, v192
	v_sub_f32_e32 v81, v81, v192
	v_exp_f32_e32 v80, v80
	v_exp_f32_e32 v81, v81
	v_add_f32_e32 v196, v196, v80
	v_add_f32_e32 v197, v197, v81
	v_cvt_pk_bf16_f32 v77, v80, v81
	ds_read_b64_tr_b16 v[148:149], v184 offset:13824
	ds_read_b64_tr_b16 v[150:151], v184 offset:14400
	ds_read_b64_tr_b16 v[152:153], v184 offset:13888
	ds_read_b64_tr_b16 v[154:155], v184 offset:14464
	ds_read_b64_tr_b16 v[156:157], v184 offset:16128
	ds_read_b64_tr_b16 v[158:159], v184 offset:16704
	ds_read_b64_tr_b16 v[160:161], v184 offset:16192
	ds_read_b64_tr_b16 v[162:163], v184 offset:16768
	ds_read_b64_tr_b16 v[164:165], v184 offset:27648
	ds_read_b64_tr_b16 v[166:167], v184 offset:28224
	ds_read_b64_tr_b16 v[168:169], v184 offset:27712
	ds_read_b64_tr_b16 v[170:171], v184 offset:28288
	s_waitcnt lgkmcnt(10)
	v_mfma_f32_32x32x16_bf16 v[116:131], v[148:151], v[2:5], 0
	s_waitcnt lgkmcnt(8)
	v_mfma_f32_32x32x16_bf16 v[132:147], v[152:155], v[2:5], 0
	ds_read_b64_tr_b16 v[172:173], v184 offset:29952
	ds_read_b64_tr_b16 v[174:175], v184 offset:30528
	ds_read_b64_tr_b16 v[176:177], v184 offset:30016
	ds_read_b64_tr_b16 v[178:179], v184 offset:30592
	s_waitcnt lgkmcnt(10)
	v_mfma_f32_32x32x16_bf16 v[116:131], v[156:159], v[10:13], v[116:131]
	s_waitcnt lgkmcnt(8)
	v_mfma_f32_32x32x16_bf16 v[132:147], v[160:163], v[10:13], v[132:147]
	ds_read_b64_tr_b16 v[148:149], v184 offset:32256
	ds_read_b64_tr_b16 v[150:151], v184 offset:32832
	ds_read_b64_tr_b16 v[152:153], v184 offset:32320
	ds_read_b64_tr_b16 v[154:155], v184 offset:32896
	s_waitcnt lgkmcnt(10)
	v_mfma_f32_32x32x16_bf16 v[116:131], v[164:167], v[18:21], v[116:131]
	s_waitcnt lgkmcnt(8)
	v_mfma_f32_32x32x16_bf16 v[132:147], v[168:171], v[18:21], v[132:147]
	ds_read_b64_tr_b16 v[156:157], v184 offset:34560
	ds_read_b64_tr_b16 v[158:159], v184 offset:35136
	ds_read_b64_tr_b16 v[160:161], v184 offset:34624
	ds_read_b64_tr_b16 v[162:163], v184 offset:35200
	s_waitcnt lgkmcnt(10)
	v_mfma_f32_32x32x16_bf16 v[116:131], v[172:175], v[26:29], v[116:131]
	s_waitcnt lgkmcnt(8)
	v_mfma_f32_32x32x16_bf16 v[132:147], v[176:179], v[26:29], v[132:147]
	ds_read_b64_tr_b16 v[164:165], v184 offset:46080
	ds_read_b64_tr_b16 v[166:167], v184 offset:46656
	ds_read_b64_tr_b16 v[168:169], v184 offset:46144
	ds_read_b64_tr_b16 v[170:171], v184 offset:46720
	s_waitcnt lgkmcnt(10)
	v_mfma_f32_32x32x16_bf16 v[116:131], v[148:151], v[34:37], v[116:131]
	s_waitcnt lgkmcnt(8)
	v_mfma_f32_32x32x16_bf16 v[132:147], v[152:155], v[34:37], v[132:147]
	ds_read_b64_tr_b16 v[172:173], v184 offset:48384
	ds_read_b64_tr_b16 v[174:175], v184 offset:48960
	ds_read_b64_tr_b16 v[176:177], v184 offset:48448
	ds_read_b64_tr_b16 v[178:179], v184 offset:49024
	s_waitcnt lgkmcnt(10)
	v_mfma_f32_32x32x16_bf16 v[116:131], v[156:159], v[42:45], v[116:131]
	s_waitcnt lgkmcnt(8)
	v_mfma_f32_32x32x16_bf16 v[132:147], v[160:163], v[42:45], v[132:147]
	ds_read_b64_tr_b16 v[148:149], v184 offset:50688
	ds_read_b64_tr_b16 v[150:151], v184 offset:51264
	ds_read_b64_tr_b16 v[152:153], v184 offset:50752
	ds_read_b64_tr_b16 v[154:155], v184 offset:51328
	s_waitcnt lgkmcnt(10)
	v_mfma_f32_32x32x16_bf16 v[116:131], v[164:167], v[50:53], v[116:131]
	s_waitcnt lgkmcnt(8)
	v_mfma_f32_32x32x16_bf16 v[132:147], v[168:171], v[50:53], v[132:147]
	ds_read_b64_tr_b16 v[156:157], v184 offset:52992
	ds_read_b64_tr_b16 v[158:159], v184 offset:53568
	ds_read_b64_tr_b16 v[160:161], v184 offset:53056
	ds_read_b64_tr_b16 v[162:163], v184 offset:53632
	s_waitcnt lgkmcnt(10)
	v_mfma_f32_32x32x16_bf16 v[116:131], v[172:175], v[58:61], v[116:131]
	s_waitcnt lgkmcnt(8)
	v_mfma_f32_32x32x16_bf16 v[132:147], v[176:179], v[58:61], v[132:147]
	s_waitcnt lgkmcnt(6)
	v_mfma_f32_32x32x16_bf16 v[116:131], v[148:151], v[66:69], v[116:131]
	s_waitcnt lgkmcnt(4)
	v_mfma_f32_32x32x16_bf16 v[132:147], v[152:155], v[66:69], v[132:147]
	s_waitcnt lgkmcnt(2)
	v_mfma_f32_32x32x16_bf16 v[116:131], v[156:159], v[74:77], v[116:131]
	s_waitcnt lgkmcnt(0)
	v_mfma_f32_32x32x16_bf16 v[132:147], v[160:163], v[74:77], v[132:147]
.Lmb_fin:
	s_nop 7
	s_nop 4
	v_add_f32_e32 v194, v194, v195
	v_add_f32_e32 v196, v196, v197
	v_add_f32_e32 v194, v194, v196
	v_mov_b32_e32 v195, v194
	s_nop 1
	v_permlane32_swap_b32_e32 v194, v195
	v_add_f32_e32 v194, v194, v195
	v_rcp_f32_e32 v195, v194
	v_log_f32_e32 v196, v194
	v_fma_f32 v197, -v194, v195, 2.0
	v_mul_f32_e32 v195, v195, v197
	v_add_f32_e32 v196, v192, v196
	v_mul_f32_e32 v116, v116, v195
	v_mul_f32_e32 v117, v117, v195
	v_mul_f32_e32 v118, v118, v195
	v_mul_f32_e32 v119, v119, v195
	v_mul_f32_e32 v120, v120, v195
	v_mul_f32_e32 v121, v121, v195
	v_mul_f32_e32 v122, v122, v195
	v_mul_f32_e32 v123, v123, v195
	v_mul_f32_e32 v124, v124, v195
	v_mul_f32_e32 v125, v125, v195
	v_mul_f32_e32 v126, v126, v195
	v_mul_f32_e32 v127, v127, v195
	v_mul_f32_e32 v128, v128, v195
	v_mul_f32_e32 v129, v129, v195
	v_mul_f32_e32 v130, v130, v195
	v_mul_f32_e32 v131, v131, v195
	v_mul_f32_e32 v132, v132, v195
	v_mul_f32_e32 v133, v133, v195
	v_mul_f32_e32 v134, v134, v195
	v_mul_f32_e32 v135, v135, v195
	v_mul_f32_e32 v136, v136, v195
	v_mul_f32_e32 v137, v137, v195
	v_mul_f32_e32 v138, v138, v195
	v_mul_f32_e32 v139, v139, v195
	v_mul_f32_e32 v140, v140, v195
	v_mul_f32_e32 v141, v141, v195
	v_mul_f32_e32 v142, v142, v195
	v_mul_f32_e32 v143, v143, v195
	v_mul_f32_e32 v144, v144, v195
	v_mul_f32_e32 v145, v145, v195
	v_mul_f32_e32 v146, v146, v195
	v_mul_f32_e32 v147, v147, v195
	v_lshlrev_b32_e32 v189, 9, v199
	v_lshl_add_u32 v189, v181, 4, v189
	v_cvt_pk_bf16_f32 v208, v116, v117
	v_cvt_pk_bf16_f32 v209, v118, v119
	v_cvt_pk_bf16_f32 v210, v120, v121
	v_cvt_pk_bf16_f32 v211, v122, v123
	s_nop 1
	v_permlane32_swap_b32_e32 v208, v210
	v_permlane32_swap_b32_e32 v209, v211
	global_store_dwordx4 v189, v[208:211], s[16:17] offset:0
	v_cvt_pk_bf16_f32 v250, v124, v125
	v_cvt_pk_bf16_f32 v251, v126, v127
	v_cvt_pk_bf16_f32 v252, v128, v129
	v_cvt_pk_bf16_f32 v253, v130, v131
	s_nop 1
	v_permlane32_swap_b32_e32 v250, v252
	v_permlane32_swap_b32_e32 v251, v253
	global_store_dwordx4 v189, v[250:253], s[16:17] offset:32
	v_cvt_pk_bf16_f32 v208, v132, v133
	v_cvt_pk_bf16_f32 v209, v134, v135
	v_cvt_pk_bf16_f32 v210, v136, v137
	v_cvt_pk_bf16_f32 v211, v138, v139
	s_nop 1
	v_permlane32_swap_b32_e32 v208, v210
	v_permlane32_swap_b32_e32 v209, v211
	global_store_dwordx4 v189, v[208:211], s[16:17] offset:64
	v_cvt_pk_bf16_f32 v250, v140, v141
	v_cvt_pk_bf16_f32 v251, v142, v143
	v_cvt_pk_bf16_f32 v252, v144, v145
	v_cvt_pk_bf16_f32 v253, v146, v147
	s_nop 1
	v_permlane32_swap_b32_e32 v250, v252
	v_permlane32_swap_b32_e32 v251, v253
	global_store_dwordx4 v189, v[250:253], s[16:17] offset:96
	v_lshlrev_b32_e32 v190, 4, v199
	v_cmp_eq_u32_e32 vcc, 0, v181
	s_nop 1
	s_and_saveexec_b64 s[38:39], vcc
	global_store_dword v190, v196, s[18:19]
	s_mov_b64 exec, s[38:39]
	s_add_i32 s21, s21, 1
	s_add_i32 s20, s20, -1
	s_cmp_eq_u32 s20, 0
	s_cbranch_scc1 .Lmb_done
	s_cmpk_gt_i32 s21, 0x5ff
	s_cbranch_scc0 .Lmb_unit

	.amdhsa_kernel _Z3fwd4Args
		.amdhsa_group_segment_fixed_size 0
		.amdhsa_private_segment_fixed_size 0
		.amdhsa_kernarg_size 392
		.amdhsa_user_sgpr_count 2
		.amdhsa_user_sgpr_dispatch_ptr 0
		.amdhsa_user_sgpr_queue_ptr 0
		.amdhsa_user_sgpr_kernarg_segment_ptr 1
		.amdhsa_user_sgpr_dispatch_id 0
		.amdhsa_user_sgpr_kernarg_preload_length 0
		.amdhsa_user_sgpr_kernarg_preload_offset 0
		.amdhsa_user_sgpr_private_segment_size 0
		.amdhsa_uses_dynamic_stack 0
		.amdhsa_enable_private_segment 0
		.amdhsa_system_sgpr_workgroup_id_x 1
		.amdhsa_system_sgpr_workgroup_id_y 0
		.amdhsa_system_sgpr_workgroup_id_z 0
		.amdhsa_system_sgpr_workgroup_info 0
		.amdhsa_system_vgpr_workitem_id 0
		.amdhsa_next_free_vgpr 256
		.amdhsa_next_free_sgpr 98
		.amdhsa_accum_offset 256
		.amdhsa_reserve_vcc 1
		.amdhsa_float_round_mode_32 0
		.amdhsa_float_round_mode_16_64 0
		.amdhsa_float_denorm_mode_32 3
		.amdhsa_float_denorm_mode_16_64 3
		.amdhsa_dx10_clamp 1
		.amdhsa_ieee_mode 1
		.amdhsa_fp16_overflow 0
		.amdhsa_tg_split 0
		.amdhsa_exception_fp_ieee_invalid_op 0
		.amdhsa_exception_fp_denorm_src 0
		.amdhsa_exception_fp_ieee_div_zero 0
		.amdhsa_exception_fp_ieee_overflow 0
		.amdhsa_exception_fp_ieee_underflow 0
		.amdhsa_exception_fp_ieee_inexact 0
		.amdhsa_exception_int_div_zero 0
	.end_amdhsa_kernel

amdhsa.kernels:
  - .agpr_count:     0
    .args:
      - .offset:         0
        .size:           136
        .value_kind:     by_value
      - .offset:         136
        .size:           4
        .value_kind:     hidden_block_count_x
      - .offset:         140
        .size:           4
        .value_kind:     hidden_block_count_y
      - .offset:         144
        .size:           4
        .value_kind:     hidden_block_count_z
      - .offset:         148
        .size:           2
        .value_kind:     hidden_group_size_x
      - .offset:         150
        .size:           2
        .value_kind:     hidden_group_size_y
      - .offset:         152
        .size:           2
        .value_kind:     hidden_group_size_z
      - .offset:         154
        .size:           2
        .value_kind:     hidden_remainder_x
      - .offset:         156
        .size:           2
        .value_kind:     hidden_remainder_y
      - .offset:         158
        .size:           2
        .value_kind:     hidden_remainder_z
      - .offset:         176
        .size:           8
        .value_kind:     hidden_global_offset_x
      - .offset:         184
        .size:           8
        .value_kind:     hidden_global_offset_y
      - .offset:         192
        .size:           8
        .value_kind:     hidden_global_offset_z
      - .offset:         200
        .size:           2
        .value_kind:     hidden_grid_dims
      - .offset:         256
        .size:           4
        .value_kind:     hidden_dynamic_lds_size
    .group_segment_fixed_size: 0
    .kernarg_segment_align: 8
    .kernarg_segment_size: 392
    .language:       OpenCL C
    .language_version:
      - 2
      - 0
    .max_flat_workgroup_size: 512
    .name:           _Z3fwd4Args
    .private_segment_fixed_size: 0
    .sgpr_count:     104
    .sgpr_spill_count: 95
    .symbol:         _Z3fwd4Args.kd
    .uniform_work_group_size: 1
    .uses_dynamic_stack: false
    .vgpr_count:     256
    .vgpr_spill_count: 0
    .wavefront_size: 64
